# diff unit map1->map2 transition: Q2 loads and map-2 tile-0 LDS-DMA issued at loop exit, stash stores global_store draining under tile 0 (vmcnt(16)), dropped redundant pre-DMA barrier
# speedup vs baseline: 1.0008x; 1.0008x over previous
.LBB0_148:
	v_ashrrev_i32_e32 v194, 6, v218
	v_and_b32_e32 v196, 31, v218
	v_lshl_or_b32 v194, v194, 5, v196
	v_ashrrev_i32_e32 v195, 31, v194
	v_lshlrev_b64 v[194:195], 10, v[194:195]
	v_lshl_add_u64 v[194:195], s[30:31], 0, v[194:195]
	v_lshl_add_u64 v[194:195], v[194:195], 0, v[184:185]
	global_load_dwordx4 v[96:99], v[194:195], off offset:128
	global_load_dwordx4 v[100:103], v[194:195], off offset:160
	global_load_dwordx4 v[104:107], v[194:195], off offset:192
	global_load_dwordx4 v[108:111], v[194:195], off offset:224
	s_sub_u32 s0, s68, s24
	s_subb_u32 s1, s69, s25
	s_add_u32 s0, s0, s78
	s_addc_u32 s1, s1, s79
	s_add_i32 m0, s5, 0x8000
	v_lshl_add_u64 v[198:199], v[116:117], 0, s[0:1]
	global_load_lds_dwordx4 v[198:199], off
	v_lshl_add_u64 v[198:199], v[112:113], 1, s[34:35]
	s_mov_b32 m0, s5
	s_nop 0
	global_load_lds_dwordx4 v[198:199], off
	v_lshl_add_u64 v[198:199], v[114:115], 1, s[34:35]
	s_add_i32 m0, s5, 0x2000
	s_nop 0
	global_load_lds_dwordx4 v[198:199], off
	s_and_saveexec_b64 s[0:1], s[6:7]
	ds_write_b32 v122, v64
	s_or_b64 exec, exec, s[0:1]
	v_lshlrev_b32_e32 v64, 6, v121
	v_ashrrev_i32_e32 v65, 31, v64
	s_waitcnt lgkmcnt(0)
	v_add_u32_e32 v80, v119, v184
	v_lshl_add_u64 v[112:113], v[64:65], 2, s[12:13]
	ds_read_b128 v[64:67], v80
	ds_read_b128 v[68:71], v80 offset:32
	s_mov_b32 s5, 0
	v_mov_b32_e32 v130, 0
	v_mov_b32_e32 v131, 0
	s_waitcnt lgkmcnt(1)
	v_rcp_f32_e32 v72, v64
	v_rcp_f32_e32 v73, v65
	v_rcp_f32_e32 v74, v66
	v_rcp_f32_e32 v75, v67
	ds_read_b128 v[64:67], v80 offset:64
	s_waitcnt lgkmcnt(1)
	v_rcp_f32_e32 v68, v68
	v_rcp_f32_e32 v69, v69
	v_rcp_f32_e32 v70, v70
	v_rcp_f32_e32 v71, v71
	s_waitcnt lgkmcnt(0)
	v_rcp_f32_e32 v76, v64
	v_rcp_f32_e32 v77, v65
	v_rcp_f32_e32 v78, v66
	v_rcp_f32_e32 v79, v67
	ds_read_b128 v[64:67], v80 offset:96
	v_pk_mul_f32 v[48:49], v[48:49], v[72:73]
	v_pk_mul_f32 v[50:51], v[50:51], v[74:75]
	v_pk_mul_f32 v[32:33], v[32:33], v[72:73]
	v_pk_mul_f32 v[34:35], v[34:35], v[74:75]
	s_waitcnt lgkmcnt(0)
	v_rcp_f32_e32 v64, v64
	v_rcp_f32_e32 v65, v65
	v_rcp_f32_e32 v66, v66
	v_rcp_f32_e32 v67, v67
	v_pk_mul_f32 v[16:17], v[16:17], v[72:73]
	v_pk_mul_f32 v[18:19], v[18:19], v[74:75]
	v_pk_mul_f32 v[0:1], v[0:1], v[72:73]
	v_pk_mul_f32 v[2:3], v[2:3], v[74:75]
	global_store_dwordx4 v[112:113], v[48:51], off
	global_store_dwordx4 v[112:113], v[32:35], off offset:64
	global_store_dwordx4 v[112:113], v[16:19], off offset:128
	v_pk_mul_f32 v[48:49], v[52:53], v[68:69]
	v_pk_mul_f32 v[50:51], v[54:55], v[70:71]
	v_pk_mul_f32 v[32:33], v[36:37], v[68:69]
	v_pk_mul_f32 v[34:35], v[38:39], v[70:71]
	v_pk_mul_f32 v[16:17], v[20:21], v[68:69]
	v_pk_mul_f32 v[18:19], v[22:23], v[70:71]
	global_store_dwordx4 v[112:113], v[0:3], off offset:192
	global_store_dwordx4 v[112:113], v[48:51], off offset:16
	global_store_dwordx4 v[112:113], v[32:35], off offset:80
	v_pk_mul_f32 v[0:1], v[4:5], v[68:69]
	v_pk_mul_f32 v[2:3], v[6:7], v[70:71]
	v_pk_mul_f32 v[48:49], v[56:57], v[76:77]
	v_pk_mul_f32 v[50:51], v[58:59], v[78:79]
	v_pk_mul_f32 v[32:33], v[40:41], v[76:77]
	v_pk_mul_f32 v[34:35], v[42:43], v[78:79]
	global_store_dwordx4 v[112:113], v[16:19], off offset:144
	global_store_dwordx4 v[112:113], v[0:3], off offset:208
	global_store_dwordx4 v[112:113], v[48:51], off offset:32
	v_pk_mul_f32 v[16:17], v[24:25], v[76:77]
	v_pk_mul_f32 v[18:19], v[26:27], v[78:79]
	v_pk_mul_f32 v[0:1], v[8:9], v[76:77]
	v_pk_mul_f32 v[2:3], v[10:11], v[78:79]
	v_pk_mul_f32 v[48:49], v[60:61], v[64:65]
	v_pk_mul_f32 v[50:51], v[62:63], v[66:67]
	global_store_dwordx4 v[112:113], v[32:35], off offset:96
	global_store_dwordx4 v[112:113], v[16:19], off offset:160
	global_store_dwordx4 v[112:113], v[0:3], off offset:224
	v_pk_mul_f32 v[32:33], v[44:45], v[64:65]
	v_pk_mul_f32 v[34:35], v[46:47], v[66:67]
	v_pk_mul_f32 v[16:17], v[28:29], v[64:65]
	v_pk_mul_f32 v[18:19], v[30:31], v[66:67]
	v_pk_mul_f32 v[0:1], v[12:13], v[64:65]
	v_pk_mul_f32 v[2:3], v[14:15], v[66:67]
	v_mov_b32_e32 v4, v218
	global_store_dwordx4 v[112:113], v[48:51], off offset:48
	global_store_dwordx4 v[112:113], v[32:35], off offset:112
	global_store_dwordx4 v[112:113], v[16:19], off offset:176
	global_store_dwordx4 v[112:113], v[0:3], off offset:240
	v_mov_b32_e32 v14, v185
	v_and_b32_e32 v6, 31, v4
	v_and_b32_e32 v0, 0x3fffffc0, v4
	v_lshl_add_u32 v122, v0, 2, s4
	v_ashrrev_i32_e32 v0, 6, v4
	v_lshrrev_b32_e32 v7, 1, v4
	v_readfirstlane_b32 s0, v0
	v_lshl_or_b32 v0, v0, 5, v6
	v_ashrrev_i32_e32 v1, 31, v0
	v_lshlrev_b64 v[0:1], 10, v[0:1]
	v_and_b32_e32 v5, 63, v4
	v_lshl_add_u64 v[0:1], s[30:31], 0, v[0:1]
	v_and_b32_e32 v184, 16, v7
	v_lshl_add_u64 v[0:1], v[0:1], 0, v[184:185]
	s_lshl_b32 s1, s0, 10
	v_lshlrev_b32_e32 v8, 4, v5
	v_or_b32_e32 v0, s1, v8
	v_ashrrev_i32_e32 v1, 31, v0
	v_lshrrev_b32_e32 v1, 25, v1
	v_add_u32_e32 v1, v0, v1
	v_lshlrev_b32_e32 v9, 3, v5
	s_lshl_b32 s0, s0, 6
	v_ashrrev_i32_e32 v2, 7, v1
	v_and_b32_e32 v1, 0xffffff80, v1
	v_and_b32_e32 v3, 32, v4
	s_and_b32 s0, s0, 64
	v_and_b32_e32 v10, 24, v9
	v_sub_u32_e32 v0, v0, v1
	v_or3_b32 v3, v10, v3, s0
	s_ashr_i32 s0, s1, 8
	v_ashrrev_i32_e32 v0, 4, v0
	v_lshrrev_b32_e32 v1, 1, v2
	s_and_b32 s4, s0, 0x7ffff0
	s_lshr_b32 s0, s0, 1
	v_bitop3_b32 v0, v1, v0, 7 bitop3:0x6c
	v_bfe_u32 v1, v4, 2, 2
	s_and_b32 s0, s0, 4
	v_and_or_b32 v1, v7, 8, v1
	s_or_b32 s0, s4, s0
	v_or_b32_e32 v10, s0, v1
	s_add_i32 s0, s1, 0x2000
	s_ashr_i32 s0, s0, 8
	s_and_b32 s4, s0, 0x7ffff0
	s_lshr_b32 s0, s0, 1
	s_and_b32 s0, s0, 4
	s_or_b32 s0, s4, s0
	v_or_b32_e32 v1, s0, v1
	v_lshl_or_b32 v116, v1, 9, v3
	v_lshlrev_b32_e32 v1, 9, v2
	v_lshl_add_u32 v0, v0, 3, v1
	v_ashrrev_i32_e32 v1, 31, v0
	v_lshlrev_b64 v[0:1], 1, v[0:1]
	v_lshl_or_b32 v114, v10, 9, v3
	v_lshl_add_u64 v[2:3], s[68:69], 0, v[0:1]
	s_add_i32 s4, s1, 0
	v_lshl_add_u64 v[2:3], v[2:3], 0, s[78:79]
	s_add_i32 m0, s4, 0x8000
	v_ashrrev_i32_e32 v115, 31, v114
	v_lshl_add_u64 v[2:3], v[114:115], 1, s[34:35]
	s_mov_b32 m0, s4
	v_ashrrev_i32_e32 v117, 31, v116
	v_lshl_add_u64 v[2:3], v[116:117], 1, s[34:35]
	s_add_i32 m0, s4, 0x2000
	s_cmp_lg_u32 0, -1
	s_cselect_b32 s0, 0, 0
	v_lshlrev_b32_e32 v10, 1, v4
	v_lshlrev_b32_e32 v4, 3, v4
	s_add_i32 s1, s0, 0x8000
	v_and_b32_e32 v4, 0x70, v4
	v_lshl_add_u32 v124, v6, 7, s1
	s_movk_i32 s1, 0x60
	v_and_b32_e32 v3, 32, v10
	v_bitop3_b32 v128, v184, v4, s1 bitop3:0x36
	s_movk_i32 s1, 0x118
	v_and_b32_e32 v2, 0xc0, v8
	v_lshl_add_u64 v[118:119], s[24:25], 0, v[0:1]
	v_and_or_b32 v0, v9, s1, v3
	v_mov_b32_e32 v15, v185
	v_bitop3_b32 v125, v7, v4, 16 bitop3:0x6c
	v_bitop3_b32 v126, v184, v4, 32 bitop3:0x36
	v_bitop3_b32 v127, v184, v4, 64 bitop3:0x36
	v_cmp_gt_u32_e64 s[6:7], 32, v5
	v_lshl_add_u32 v123, v6, 2, v122
	v_add3_u32 v129, v2, s0, v0
	v_mov_b32_e32 v0, v185
	v_mov_b32_e32 v1, v185
	v_mov_b32_e32 v2, v185
	v_mov_b32_e32 v3, v185
	v_mov_b32_e32 v4, v185
	v_mov_b32_e32 v5, v185
	v_mov_b32_e32 v6, v185
	v_mov_b32_e32 v7, v185
	v_mov_b32_e32 v8, v185
	v_mov_b32_e32 v9, v185
	v_mov_b32_e32 v10, v185
	v_mov_b32_e32 v11, v185
	v_mov_b32_e32 v12, v185
	v_mov_b32_e32 v13, v185
	v_mov_b64_e32 v[30:31], v[14:15]
	v_mov_b64_e32 v[46:47], v[14:15]
	v_mov_b64_e32 v[62:63], v[14:15]
	v_mov_b64_e32 v[28:29], v[12:13]
	v_mov_b64_e32 v[26:27], v[10:11]
	v_mov_b64_e32 v[24:25], v[8:9]
	v_mov_b64_e32 v[22:23], v[6:7]
	v_mov_b64_e32 v[20:21], v[4:5]
	v_mov_b64_e32 v[18:19], v[2:3]
	v_mov_b64_e32 v[16:17], v[0:1]
	v_mov_b64_e32 v[44:45], v[12:13]
	v_mov_b64_e32 v[42:43], v[10:11]
	v_mov_b64_e32 v[40:41], v[8:9]
	v_mov_b64_e32 v[38:39], v[6:7]
	v_mov_b64_e32 v[36:37], v[4:5]
	v_mov_b64_e32 v[34:35], v[2:3]
	v_mov_b64_e32 v[32:33], v[0:1]
	v_mov_b64_e32 v[60:61], v[12:13]
	v_mov_b64_e32 v[58:59], v[10:11]
	v_mov_b64_e32 v[56:57], v[8:9]
	v_mov_b64_e32 v[54:55], v[6:7]
	v_mov_b64_e32 v[52:53], v[4:5]
	v_mov_b64_e32 v[50:51], v[2:3]
	v_mov_b64_e32 v[48:49], v[0:1]
	v_mov_b32_e32 v160, 0x80000000
	v_mov_b32_e32 v161, 0x80000000
	v_mov_b32_e32 v162, 0x80000000
	v_mov_b32_e32 v163, 0x80000000
	v_mov_b32_e32 v164, 0x80000000
	v_mov_b32_e32 v165, 0x80000000
	v_mov_b32_e32 v166, 0x80000000
	v_mov_b32_e32 v167, 0x80000000
	v_mov_b32_e32 v168, 0x80000000
	v_mov_b32_e32 v169, 0x80000000
	v_mov_b32_e32 v170, 0x80000000
	v_mov_b32_e32 v171, 0x80000000
	v_mov_b32_e32 v172, 0x80000000
	v_mov_b32_e32 v173, 0x80000000
	v_mov_b32_e32 v174, 0x80000000
	v_mov_b32_e32 v175, 0x80000000
	v_readlane_b32 s54, v254, 48
	s_waitcnt vmcnt(16) lgkmcnt(0)
	s_barrier
	s_and_b32 s53, s5, 1
	v_add_u32_e32 v120, v124, v125
	ds_read_b128 v[132:135], v120 offset:0
	ds_read_b128 v[136:139], v120 offset:0x1000
	s_cmp_eq_u32 s5, 31
	s_movk_i32 s0, 0x2000
	s_cbranch_scc1 .LBB0_152
